# first grid barrier: the 16 census counters are read with 16 loads in flight instead of one at a time
# baseline (speedup 1.0000x reference)
; __device__ __forceinline__ unsigned xb_ld(unsigned* p)              { return __hip_atomic_load(p, __ATOMIC_RELAXED, __HIP_MEMORY_SCOPE_AGENT); }
; __device__ __forceinline__ void xcd_barrier_complete(unsigned* bar, unsigned x, unsigned& nloc, unsigned& nx) {
;     const unsigned G = gridDim.x * gridDim.y * gridDim.z;
;     unsigned sum, cnt, mine, sp = 0u;
;     for (;;) {
;         sum = 0u; cnt = 0u; mine = 0u;
; #pragma unroll
;         for (unsigned jx = 0; jx < 16; ++jx) { const unsigned c = xb_ld(&bar[XB_XCNT(jx)]); sum += c; cnt += (c > 0u) ? 1u : 0u; mine = (jx == x) ? c : mine; }
;         if (sum == G) break;
;         __builtin_amdgcn_s_sleep(1);
;         if ((++sp & 255u) == 0u) { if (xb_ld(&bar[XB_TMO])) break; if (sp > XB_SPIN_CAP) { atomicAdd(&bar[XB_TMO], 1u); break; } }
;     }
;     nloc = mine > 0u ? mine : 1u; nx = cnt > 0u ? cnt : 1u;
; }
.LBB0_22:
	global_load_dword v2, v3, s[80:81] sc1
	global_load_dword v1, v3, s[80:81] offset:256 sc1
	global_load_dword v4, v3, s[80:81] offset:512 sc1
	global_load_dword v5, v3, s[80:81] offset:768 sc1
	global_load_dword v10, v3, s[80:81] offset:1024 sc1
	global_load_dword v11, v3, s[80:81] offset:1280 sc1
	global_load_dword v12, v3, s[80:81] offset:1536 sc1
	global_load_dword v13, v3, s[80:81] offset:1792 sc1
	global_load_dword v14, v3, s[80:81] offset:2048 sc1
	global_load_dword v15, v3, s[80:81] offset:2304 sc1
	global_load_dword v16, v3, s[80:81] offset:2560 sc1
	global_load_dword v17, v3, s[80:81] offset:2816 sc1
	global_load_dword v18, v3, s[80:81] offset:3072 sc1
	global_load_dword v19, v3, s[80:81] offset:3328 sc1
	global_load_dword v20, v3, s[80:81] offset:3584 sc1
	global_load_dword v21, v3, s[80:81] offset:3840 sc1
	s_mov_b64 s[8:9], -1
	s_mov_b64 s[6:7], -1
	s_waitcnt vmcnt(0)
	v_add_u32_e32 v22, v1, v2
	v_add_u32_e32 v22, v22, v4
	v_add_u32_e32 v22, v22, v5
	v_add_u32_e32 v22, v22, v10
	v_add_u32_e32 v22, v22, v11
	v_add_u32_e32 v22, v22, v12
	v_add_u32_e32 v22, v22, v13
	v_add_u32_e32 v22, v22, v14
	v_add_u32_e32 v22, v22, v15
	v_add_u32_e32 v22, v22, v16
	v_add_u32_e32 v22, v22, v17
	v_add_u32_e32 v22, v22, v18
	v_add_u32_e32 v22, v22, v19
	v_add_u32_e32 v22, v22, v20
	v_add_u32_e32 v22, v22, v21
	v_cmp_eq_u32_e32 vcc, s3, v22
	s_cbranch_vccnz .LBB0_21
	s_and_b32 s6, s12, 0xff
	s_cmp_eq_u32 s6, 0
	s_mov_b64 s[6:7], -1
	s_mov_b64 s[10:11], -1
	s_sleep 1
	s_cbranch_scc1 .LBB0_26
	s_and_b64 vcc, exec, s[10:11]
	s_cbranch_vccz .LBB0_21
